# v64 plus one static s_setprio 1 for waves 0-2 (the MFMA/P-store waves) during hg_prepass
# baseline (speedup 1.0000x reference)
; __device__ __forceinline__ const float* karg_in(int i) { karg_ptr_t kp = (karg_ptr_t)__builtin_amdgcn_kernarg_segment_ptr(); asm volatile("" : "+s"(kp)); return *(const float* __attribute__((address_space(4))) const*)(kp + 8 * i); }
; #define WSB karg_ws()
; __global__ void __launch_bounds__(512, 2) fwd_megakernel(Params p) {
;     ...
;     if constexpr (PH_MASK & 16) hg_prepass(lds, QF, karg_in(7), (bf16_t*)(WSB + WS_P), (float*)(WSB + WS_ER), G, bid);
.Lp4_done:
	v_lshrrev_b32_e32 v0, 6, v218
	s_nop 0
	v_readfirstlane_b32 s4, v0
	s_nop 3
	s_cmp_lt_u32 s4, 3
	s_cbranch_scc0 .Lpp_prio_done
	s_setprio 1

; #define LDS_BARRIER() do { asm volatile("s_waitcnt lgkmcnt(0)" ::: "memory"); __builtin_amdgcn_s_barrier(); asm volatile("" ::: "memory"); } while (0)
; __device__ __forceinline__ void hg_prepass(LAS unsigned char* lds, bf16_t* QF, const float* lbtab, bf16_t* P, float* Dg, int G, int bid) {
;     ...
;     LDS_BARRIER();
; __global__ void __launch_bounds__(512, 2) fwd_megakernel(Params p) {
;     ...
;     grid.sync();
.LBB0_382:
	s_setprio 0
	s_waitcnt lgkmcnt(0)
	s_barrier
	s_waitcnt lgkmcnt(0)
	s_waitcnt vmcnt(0)
	s_barrier
	s_and_saveexec_b64 s[8:9], s[72:73]
	s_cbranch_execz .LBB0_392
	buffer_wbl2 sc1
	s_waitcnt vmcnt(0)
	s_load_dwordx2 s[10:11], s[0:1], 0xc8
	s_load_dword s12, s[0:1], 0xd0
	v_mov_b32_e32 v2, 0
	v_mov_b32_e32 v1, 1
	s_waitcnt lgkmcnt(0)
	s_add_u32 s10, s10, 0x100000
	s_addc_u32 s11, s11, 0
	s_mul_i32 s12, s12, 4
	global_atomic_add v2, v1, s[10:11]
